# E2: attention main loops write last QK MFMA with D!=C (removes 16 v_mov_b64 + nops per iteration)
# baseline (speedup 1.0000x reference)
; #define LAS __attribute__((address_space(3)))
; __device__ __forceinline__ unsigned cvt_pk(float lo, float hi) { unsigned r; asm volatile("v_cvt_pk_bf16_f32 %0, %1, %2" : "=v"(r) : "v"(lo), "v"(hi)); return r; }
; __device__ __forceinline__ void attn_unit(LAS unsigned char* lds, int b, int h, int q0, int kbeg, int ntiles, const bf16_t* Q, const bf16_t* K, const bf16_t* Vt, bf16_t* cat) {
;     ...
;         const LAS unsigned char* kb = lds + (buf ^ 1) * AK_BYTES + r32 * (KP * 2) + hi * 16;
;         f32x16 pn0, pn1;
; #pragma unroll
;         for (int r = 0; r < 16; ++r) { pn0[r] = 0.f; pn1[r] = 0.f; }
;         float ps = 0.f; u32x4 pw[4];
;         bf16x8 ka = *(const LAS bf16x8*)(kb), kbb = *(const LAS bf16x8*)(kb + 32 * (KP * 2));
; #pragma unroll
;         for (int ds = 0; ds < 12; ++ds) {
;             bf16x8 na = ka, nb = kbb;
;             if (ds < 11) { na = *(const LAS bf16x8*)(kb + (ds + 1) * 32); nb = *(const LAS bf16x8*)(kb + 32 * (KP * 2) + (ds + 1) * 32); }
;             pn0 = __builtin_amdgcn_mfma_f32_32x32x16_bf16(ka, qf[ds], pn0, 0, 0, 0);
;             pn1 = __builtin_amdgcn_mfma_f32_32x32x16_bf16(kbb, qf[ds], pn1, 0, 0, 0);
;             if (ds < 8) {
;                 float e[4];
; #pragma unroll
;                 for (int j = 0; j < 4; ++j) { const float v = ds < 4 ? pc0[4 * ds + j] : pc1[4 * (ds - 4) + j]; e[j] = __builtin_amdgcn_exp2f(v - mrun); }
;                 ps += (e[0] + e[1]) + (e[2] + e[3]);
;                 const unsigned w0 = cvt_pk(e[0], e[1]), w1 = cvt_pk(e[2], e[3]);
;                 if ((ds & 1) == 0) { pw[ds >> 1].x = w0; pw[ds >> 1].y = w1; } else { pw[ds >> 1].z = w0; pw[ds >> 1].w = w1; }
;             }
;             ka = na; kbb = nb;
;             __builtin_amdgcn_sched_barrier(0);
;         }
.LBB0_814:
	s_xor_b32 s6, s5, 1
	s_mul_i32 s7, s6, 0x6400
	v_add_u32_e32 v236, s7, v228
	ds_read_b128 v[98:101], v236
	v_sub_f32_e32 v82, v82, v230
	v_exp_f32_e32 v197, v82
	v_sub_f32_e32 v82, v84, v230
	v_exp_f32_e32 v201, v82
	v_sub_f32_e32 v82, v85, v230
	v_exp_f32_e32 v233, v82
	v_sub_f32_e32 v82, v86, v230
	v_exp_f32_e32 v196, v82
	v_sub_f32_e32 v82, v87, v230
	s_waitcnt lgkmcnt(0)
	v_mfma_f32_32x32x16_bf16 v[98:113], v[98:101], v[174:177], 0
	v_exp_f32_e32 v198, v82
	v_sub_f32_e32 v82, v88, v230
	v_sub_f32_e32 v83, v83, v230
	v_exp_f32_e32 v200, v82
	v_sub_f32_e32 v82, v89, v230
	v_exp_f32_e32 v199, v83
	v_exp_f32_e32 v232, v82
	ds_read_b128 v[188:191], v236 offset:32
	ds_read_b128 v[114:117], v236 offset:12800
	ds_read_b128 v[192:195], v236 offset:12832
	s_add_i32 s4, s4, 1
	v_pk_add_f32 v[82:83], v[196:197], v[198:199]
	v_pk_add_f32 v[84:85], v[200:201], v[232:233]
	s_waitcnt lgkmcnt(0)
	v_mfma_f32_32x32x16_bf16 v[114:129], v[114:117], v[174:177], 0
	v_add_f32_e64 v234, v82, v84
	v_add_f32_e64 v235, v83, v85
	v_cvt_pk_bf16_f32 v186, v197, v199
	v_cvt_pk_bf16_f32 v187, v201, v233
	v_add_f32_e32 v235, 0, v235
	v_mfma_f32_32x32x16_bf16 v[98:113], v[188:191], v[170:173], v[98:113]
	ds_read_b128 v[82:85], v236 offset:64
	ds_read_b128 v[86:89], v236 offset:12864
	v_add_f32_e32 v197, v234, v235
	v_cvt_pk_bf16_f32 v188, v196, v198
	v_cvt_pk_bf16_f32 v189, v200, v232
	v_mfma_f32_32x32x16_bf16 v[114:129], v[192:195], v[170:173], v[114:129]
	v_sub_f32_e32 v90, v90, v230
	s_waitcnt lgkmcnt(0)
	v_mfma_f32_32x32x16_bf16 v[98:113], v[82:85], v[166:169], v[98:113]
	v_exp_f32_e32 v190, v90
	v_sub_f32_e32 v90, v91, v230
	v_exp_f32_e32 v192, v90
	v_sub_f32_e32 v90, v92, v230
	v_sub_f32_e32 v82, v93, v230
	v_exp_f32_e32 v191, v90
	v_exp_f32_e32 v193, v82
	ds_read_b128 v[82:85], v236 offset:96
	ds_read_b128 v[90:93], v236 offset:12896
	v_mfma_f32_32x32x16_bf16 v[114:129], v[86:89], v[166:169], v[114:129]
	v_add_f32_e64 v194, v190, v192
	v_add_f32_e64 v195, v191, v193
	v_add_f32_e64 v198, v194, v194
	v_add_f32_e64 v199, v194, v195
	v_cvt_pk_bf16_f32 v190, v190, v192
	v_cvt_pk_bf16_f32 v191, v191, v193
	v_sub_f32_e32 v86, v94, v230
	s_waitcnt lgkmcnt(0)
	v_mfma_f32_32x32x16_bf16 v[98:113], v[82:85], v[162:165], v[98:113]
	v_exp_f32_e32 v94, v86
	v_sub_f32_e32 v86, v95, v230
	v_exp_f32_e32 v192, v86
	v_sub_f32_e32 v86, v96, v230
	v_sub_f32_e32 v82, v97, v230
	v_exp_f32_e32 v96, v86
	v_exp_f32_e32 v193, v82
	ds_read_b128 v[82:85], v236 offset:128
	ds_read_b128 v[86:89], v236 offset:12928
	v_add_f32_e32 v95, v94, v192
	v_cvt_pk_bf16_f32 v192, v94, v192
	v_add_f32_e32 v97, v96, v193
	v_mfma_f32_32x32x16_bf16 v[114:129], v[90:93], v[162:165], v[114:129]
	v_cvt_pk_bf16_f32 v193, v96, v193
	v_sub_f32_e32 v66, v66, v230
	v_exp_f32_e32 v94, v66
	v_sub_f32_e32 v66, v67, v230
	v_exp_f32_e32 v96, v66
	v_sub_f32_e32 v66, v68, v230
	v_exp_f32_e32 v198, v66
	s_waitcnt lgkmcnt(0)
	v_mfma_f32_32x32x16_bf16 v[98:113], v[82:85], v[158:161], v[98:113]
	v_sub_f32_e32 v66, v69, v230
	v_exp_f32_e32 v196, v66
	ds_read_b128 v[66:69], v236 offset:160
	ds_read_b128 v[82:85], v236 offset:12960
	v_pk_add_f32 v[90:91], v[94:95], v[96:97]
	v_cvt_pk_bf16_f32 v194, v94, v96
	v_pk_add_f32 v[92:93], v[198:199], v[196:197]
	v_cvt_pk_bf16_f32 v195, v198, v196
	v_mfma_f32_32x32x16_bf16 v[114:129], v[86:89], v[158:161], v[114:129]
	v_add_f32_e64 v90, v90, v92
	v_add_f32_e64 v91, v91, v93
	v_add_f32_e64 v86, v90, v90
	v_add_f32_e64 v87, v90, v91
	v_sub_f32_e32 v70, v70, v230
	v_exp_f32_e32 v88, v70
	v_sub_f32_e32 v70, v71, v230
	s_waitcnt lgkmcnt(0)
	v_mfma_f32_32x32x16_bf16 v[98:113], v[66:69], v[154:157], v[98:113]
	v_exp_f32_e32 v90, v70
	v_sub_f32_e32 v70, v72, v230
	v_sub_f32_e32 v66, v73, v230
	v_exp_f32_e32 v89, v70
	v_exp_f32_e32 v91, v66
	ds_read_b128 v[66:69], v236 offset:192
	ds_read_b128 v[70:73], v236 offset:12992
	v_cvt_pk_bf16_f32 v196, v88, v90
	v_mfma_f32_32x32x16_bf16 v[114:129], v[82:85], v[154:157], v[114:129]
	v_add_f32_e64 v92, v88, v90
	v_add_f32_e64 v93, v89, v91
	v_cvt_pk_bf16_f32 v197, v89, v91
	v_pk_add_f32 v[92:93], v[92:93], v[92:93] op_sel_hi:[0,1]
	v_sub_f32_e32 v74, v74, v230
	s_waitcnt lgkmcnt(0)
	v_mfma_f32_32x32x16_bf16 v[98:113], v[66:69], v[150:153], v[98:113]
	v_exp_f32_e32 v82, v74
	v_sub_f32_e32 v74, v75, v230
	v_exp_f32_e32 v84, v74
	v_sub_f32_e32 v74, v76, v230
	v_sub_f32_e32 v66, v77, v230
	v_exp_f32_e32 v86, v74
	v_exp_f32_e32 v88, v66
	ds_read_b128 v[66:69], v236 offset:224
	ds_read_b128 v[74:77], v236 offset:13024
	v_add_f32_e32 v83, v82, v84
	v_cvt_pk_bf16_f32 v198, v82, v84
	v_add_f32_e32 v85, v86, v88
	v_mfma_f32_32x32x16_bf16 v[114:129], v[70:73], v[150:153], v[114:129]
	v_cvt_pk_bf16_f32 v199, v86, v88
	v_sub_f32_e32 v70, v78, v230
	v_exp_f32_e32 v82, v70
	v_sub_f32_e32 v70, v79, v230
	s_waitcnt lgkmcnt(0)
	v_mfma_f32_32x32x16_bf16 v[98:113], v[66:69], v[146:149], v[98:113]
	v_exp_f32_e32 v84, v70
	v_sub_f32_e32 v70, v80, v230
	v_sub_f32_e32 v66, v81, v230
	v_exp_f32_e32 v92, v70
	v_exp_f32_e32 v86, v66
	ds_read_b128 v[66:69], v236 offset:256
	ds_read_b128 v[70:73], v236 offset:13056
	v_pk_add_f32 v[78:79], v[82:83], v[84:85]
	v_mfma_f32_32x32x16_bf16 v[114:129], v[74:77], v[146:149], v[114:129]
	v_add_f32_e64 v80, v92, v86
	v_add_f32_e64 v81, v93, v87
	v_cvt_pk_bf16_f32 v200, v82, v84
	v_cvt_pk_bf16_f32 v201, v92, v86
	v_add_f32_e64 v78, v78, v80
	v_add_f32_e64 v79, v79, v81
	v_add_f32_e32 v237, v78, v79
	s_waitcnt lgkmcnt(0)
; #define LAS __attribute__((address_space(3)))
; __device__ __forceinline__ unsigned cvt_pk(float lo, float hi) { unsigned r; asm volatile("v_cvt_pk_bf16_f32 %0, %1, %2" : "=v"(r) : "v"(lo), "v"(hi)); return r; }
; __device__ __forceinline__ void attn_unit(LAS unsigned char* lds, int b, int h, int q0, int kbeg, int ntiles, const bf16_t* Q, const bf16_t* K, const bf16_t* Vt, bf16_t* cat) {
;     ...
;         for (int ds = 0; ds < 12; ++ds) {
;             bf16x8 na = ka, nb = kbb;
;             if (ds < 11) { na = *(const LAS bf16x8*)(kb + (ds + 1) * 32); nb = *(const LAS bf16x8*)(kb + 32 * (KP * 2) + (ds + 1) * 32); }
;             pn0 = __builtin_amdgcn_mfma_f32_32x32x16_bf16(ka, qf[ds], pn0, 0, 0, 0);
;             pn1 = __builtin_amdgcn_mfma_f32_32x32x16_bf16(kbb, qf[ds], pn1, 0, 0, 0);
;             if (ds < 8) {
;                 float e[4];
; #pragma unroll
;                 for (int j = 0; j < 4; ++j) { const float v = ds < 4 ? pc0[4 * ds + j] : pc1[4 * (ds - 4) + j]; e[j] = __builtin_amdgcn_exp2f(v - mrun); }
;                 ps += (e[0] + e[1]) + (e[2] + e[3]);
;                 const unsigned w0 = cvt_pk(e[0], e[1]), w1 = cvt_pk(e[2], e[3]);
;                 if ((ds & 1) == 0) { pw[ds >> 1].x = w0; pw[ds >> 1].y = w1; } else { pw[ds >> 1].z = w0; pw[ds >> 1].w = w1; }
;             }
;             ka = na; kbb = nb;
;             __builtin_amdgcn_sched_barrier(0);
;         }
;         lrun += ps;
;         const LAS unsigned char* vb = lds + 2 * AK_BYTES + buf * AV_BYTES + r32 * AV_PITCH + hi * 8;
; #pragma unroll
;         for (int d = 0; d < 4; ++d)
; #pragma unroll
;             for (int ks = 0; ks < 4; ++ks) {
;                 const s16x4 lo = *(const LAS s16x4*)(vb + d * 32 * AV_PITCH + ks * 32), hh = *(const LAS s16x4*)(vb + d * 32 * AV_PITCH + ks * 32 + 16);
;                 const bf16x8 vf = (bf16x8){lo[0], lo[1], lo[2], lo[3], hh[0], hh[1], hh[2], hh[3]};
;                 o[d] = __builtin_amdgcn_mfma_f32_32x32x16_bf16(vf, __builtin_bit_cast(bf16x8, pw[ks]), o[d], 0, 0, 0);
;             }
;         { float mx = fmaxf(pn0[0], pn1[0]);
; #pragma unroll
;           for (int r = 1; r < 16; ++r) mx = fmaxf(mx, fmaxf(pn0[r], pn1[r]));
;           mxc = fmaxf(mx, __shfl_xor(mx, 32)); }
;         if (kt + 1 < ntiles) ASTOREV(buf ^ 1);
;         asm volatile("s_waitcnt vmcnt(0)" ::: "memory");
;         __syncthreads();
	v_mfma_f32_32x32x16_bf16 v[98:113], v[66:69], v[142:145], v[98:113]
	ds_read_b128 v[66:69], v236 offset:288
	ds_read_b128 v[74:77], v236 offset:13088
	v_mfma_f32_32x32x16_bf16 v[114:129], v[70:73], v[142:145], v[114:129]
	s_waitcnt lgkmcnt(0)
	v_mfma_f32_32x32x16_bf16 v[98:113], v[66:69], v[138:141], v[98:113]
	ds_read_b128 v[66:69], v236 offset:320
	ds_read_b128 v[70:73], v236 offset:13120
	v_mfma_f32_32x32x16_bf16 v[114:129], v[74:77], v[138:141], v[114:129]
	s_waitcnt lgkmcnt(0)
	v_mfma_f32_32x32x16_bf16 v[98:113], v[66:69], v[134:137], v[98:113]
	ds_read_b128 v[66:69], v236 offset:352
	ds_read_b128 v[232:235], v236 offset:13152
	v_mfma_f32_32x32x16_bf16 v[114:129], v[70:73], v[134:137], v[114:129]
	s_waitcnt lgkmcnt(0)
	v_mfma_f32_32x32x16_bf16 v[82:97], v[66:69], v[130:133], v[98:113]
	v_mfma_f32_32x32x16_bf16 v[66:81], v[232:235], v[130:133], v[114:129]
	s_mulk_i32 s5, 0x4400
	v_add_u32_e32 v232, s5, v229
	v_add_u32_e32 v102, 0xc800, v232
	ds_read2_b64 v[98:101], v102 offset1:2
	v_add_u32_e32 v110, 0xd800, v232
	v_add_u32_e32 v126, 0xe800, v232
	s_nop 5
	v_max_f32_e32 v238, v67, v67
	v_max_f32_e32 v239, v83, v83
	v_max_f32_e32 v238, v239, v238
	v_max3_f32 v238, v82, v66, v238
	v_add_u32_e32 v236, 0xf800, v232
	s_mulk_i32 s6, 0x4400
	s_waitcnt lgkmcnt(0)
	v_mfma_f32_32x32x16_bf16 v[50:65], v[98:101], v[186:189], v[50:65]
	ds_read2_b64 v[98:101], v102 offset0:4 offset1:6
	v_add_f32_e32 v202, v202, v237
	v_lshl_add_u64 v[212:213], v[212:213], 0, s[60:61]
	v_lshl_add_u64 v[214:215], v[214:215], 0, s[60:61]
	v_lshl_add_u64 v[216:217], v[216:217], 0, s[60:61]
	v_lshl_add_u64 v[218:219], v[218:219], 0, s[60:61]
	v_lshl_add_u64 v[220:221], v[220:221], 0, s[66:67]
	s_cmp_lg_u32 s4, 34
	s_waitcnt lgkmcnt(0)
	v_mfma_f32_32x32x16_bf16 v[50:65], v[98:101], v[190:193], v[50:65]
	ds_read2_b64 v[98:101], v102 offset0:8 offset1:10
	s_waitcnt lgkmcnt(0)
	v_mfma_f32_32x32x16_bf16 v[50:65], v[98:101], v[194:197], v[50:65]
	ds_read2_b64 v[98:101], v102 offset0:12 offset1:14
	ds_read2_b64 v[102:105], v110 offset0:32 offset1:34
	s_waitcnt lgkmcnt(0)
	v_mfma_f32_32x32x16_bf16 v[34:49], v[102:105], v[186:189], v[34:49]
	v_mfma_f32_32x32x16_bf16 v[50:65], v[98:101], v[198:201], v[50:65]
	ds_read2_b64 v[98:101], v110 offset0:36 offset1:38
	ds_read2_b64 v[106:109], v110 offset0:40 offset1:42
	ds_read2_b64 v[110:113], v110 offset0:44 offset1:46
	ds_read2_b64 v[114:117], v126 offset0:64 offset1:66
	ds_read2_b64 v[118:121], v126 offset0:68 offset1:70
	ds_read2_b64 v[122:125], v126 offset0:72 offset1:74
	ds_read2_b64 v[126:129], v126 offset0:76 offset1:78
	ds_read2_b64 v[102:105], v236 offset0:96 offset1:98
	ds_read2_b64 v[232:235], v236 offset0:100 offset1:102
	s_waitcnt lgkmcnt(0)
	v_mfma_f32_32x32x16_bf16 v[34:49], v[98:101], v[190:193], v[34:49]
	v_max_f32_e32 v98, v68, v68
	v_max_f32_e32 v99, v84, v84
	v_max_f32_e32 v98, v99, v98
	v_max_f32_e32 v99, v69, v69
	v_max_f32_e32 v100, v85, v85
	v_max_f32_e32 v99, v100, v99
	v_max3_f32 v98, v238, v98, v99
	v_max_f32_e32 v99, v70, v70
	v_max_f32_e32 v100, v86, v86
	v_max_f32_e32 v99, v100, v99
	v_max_f32_e32 v100, v71, v71
	v_max_f32_e32 v101, v87, v87
	v_max_f32_e32 v100, v101, v100
	v_max3_f32 v98, v98, v99, v100
	v_max_f32_e32 v99, v72, v72
	v_max_f32_e32 v100, v88, v88
	v_max_f32_e32 v99, v100, v99
	v_max_f32_e32 v100, v73, v73
	v_max_f32_e32 v101, v89, v89
	v_max_f32_e32 v100, v101, v100
	v_max3_f32 v98, v98, v99, v100
	v_mfma_f32_32x32x16_bf16 v[18:33], v[114:117], v[186:189], v[18:33]
	v_max_f32_e32 v99, v74, v74
	v_max_f32_e32 v100, v90, v90
	v_max_f32_e32 v99, v100, v99
	v_max_f32_e32 v100, v75, v75
	v_max_f32_e32 v101, v91, v91
	v_max_f32_e32 v100, v101, v100
	v_max3_f32 v98, v98, v99, v100
	v_mfma_f32_32x32x16_bf16 v[2:17], v[102:105], v[186:189], v[2:17]
	v_max_f32_e32 v99, v76, v76
	v_max_f32_e32 v100, v92, v92
	v_max_f32_e32 v99, v100, v99
	v_max_f32_e32 v100, v77, v77
	v_max_f32_e32 v101, v93, v93
	v_max_f32_e32 v100, v101, v100
	v_max3_f32 v98, v98, v99, v100
	v_max_f32_e32 v99, v78, v78
	v_max_f32_e32 v100, v94, v94
	v_max_f32_e32 v99, v100, v99
	v_max_f32_e32 v100, v79, v79
	v_max_f32_e32 v101, v95, v95
	v_mfma_f32_32x32x16_bf16 v[18:33], v[118:121], v[190:193], v[18:33]
	v_max_f32_e32 v100, v101, v100
	v_max3_f32 v98, v98, v99, v100
	v_max_f32_e32 v99, v80, v80
	v_max_f32_e32 v100, v96, v96
	v_max_f32_e32 v99, v100, v99
	v_max_f32_e32 v100, v81, v81
	v_max_f32_e32 v101, v97, v97
	v_mfma_f32_32x32x16_bf16 v[2:17], v[232:235], v[190:193], v[2:17]
	v_max_f32_e32 v100, v101, v100
	v_max3_f32 v98, v98, v99, v100
	ds_bpermute_b32 v99, v207, v98
	s_waitcnt lgkmcnt(0)
	v_max_f32_e32 v99, v99, v99
	v_mfma_f32_32x32x16_bf16 v[34:49], v[106:109], v[194:197], v[34:49]
	ds_read2_b64 v[100:103], v236 offset0:104 offset1:106
	ds_read2_b64 v[104:107], v236 offset0:108 offset1:110
	v_max_f32_e32 v98, v98, v99
	v_add_u32_e32 v99, s6, v231
	v_add_u32_e32 v108, 0xc800, v99
	v_add_u32_e32 v99, 0xea00, v99
	s_waitcnt vmcnt(0)
	ds_write2_b64 v108, v[178:179], v[180:181] offset1:1
	ds_write2_b64 v99, v[182:183], v[184:185] offset1:1
	s_waitcnt vmcnt(0)
	v_mfma_f32_32x32x16_bf16 v[18:33], v[122:125], v[194:197], v[18:33]
	s_waitcnt lgkmcnt(0)
	s_barrier
	v_mfma_f32_32x32x16_bf16 v[2:17], v[100:103], v[194:197], v[2:17]
	v_mfma_f32_32x32x16_bf16 v[34:49], v[110:113], v[198:201], v[34:49]
	v_mfma_f32_32x32x16_bf16 v[18:33], v[126:129], v[198:201], v[18:33]
	v_mfma_f32_32x32x16_bf16 v[2:17], v[104:107], v[198:201], v[2:17]
	s_cbranch_scc0 .LBB0_819

; #define LAS __attribute__((address_space(3)))
; __device__ __forceinline__ unsigned cvt_pk(float lo, float hi) { unsigned r; asm volatile("v_cvt_pk_bf16_f32 %0, %1, %2" : "=v"(r) : "v"(lo), "v"(hi)); return r; }
; __device__ __forceinline__ void attn_unit(LAS unsigned char* lds, int b, int h, int q0, int kbeg, int ntiles, const bf16_t* Q, const bf16_t* K, const bf16_t* Vt, bf16_t* cat) {
;     ...
;         const LAS unsigned char* kb = lds + (buf ^ 1) * AK_BYTES + r32 * (KP * 2) + hi * 16;
;         f32x16 pn0, pn1;
; #pragma unroll
;         for (int r = 0; r < 16; ++r) { pn0[r] = 0.f; pn1[r] = 0.f; }
;         float ps = 0.f; u32x4 pw[4];
;         bf16x8 ka = *(const LAS bf16x8*)(kb), kbb = *(const LAS bf16x8*)(kb + 32 * (KP * 2));
; #pragma unroll
;         for (int ds = 0; ds < 12; ++ds) {
;             bf16x8 na = ka, nb = kbb;
;             if (ds < 11) { na = *(const LAS bf16x8*)(kb + (ds + 1) * 32); nb = *(const LAS bf16x8*)(kb + 32 * (KP * 2) + (ds + 1) * 32); }
;             pn0 = __builtin_amdgcn_mfma_f32_32x32x16_bf16(ka, qf[ds], pn0, 0, 0, 0);
;             pn1 = __builtin_amdgcn_mfma_f32_32x32x16_bf16(kbb, qf[ds], pn1, 0, 0, 0);
;             if (ds < 8) {
;                 float e[4];
; #pragma unroll
;                 for (int j = 0; j < 4; ++j) { const float v = ds < 4 ? pc0[4 * ds + j] : pc1[4 * (ds - 4) + j]; e[j] = __builtin_amdgcn_exp2f(v - mrun); }
;                 ps += (e[0] + e[1]) + (e[2] + e[3]);
;                 const unsigned w0 = cvt_pk(e[0], e[1]), w1 = cvt_pk(e[2], e[3]);
;                 if ((ds & 1) == 0) { pw[ds >> 1].x = w0; pw[ds >> 1].y = w1; } else { pw[ds >> 1].z = w0; pw[ds >> 1].w = w1; }
;             }
;             ka = na; kbb = nb;
;             __builtin_amdgcn_sched_barrier(0);
;         }
.LBB0_1840:
	s_xor_b32 s6, s5, 1
	s_mul_i32 s7, s6, 0x6400
	v_add_u32_e32 v233, s7, v229
	ds_read_b128 v[98:101], v233
	v_sub_f32_e32 v82, v82, v231
	v_exp_f32_e32 v197, v82
	v_sub_f32_e32 v82, v84, v231
	v_exp_f32_e32 v201, v82
	v_sub_f32_e32 v82, v85, v231
	v_exp_f32_e32 v235, v82
	v_sub_f32_e32 v82, v86, v231
	v_exp_f32_e32 v196, v82
	v_sub_f32_e32 v82, v87, v231
	s_waitcnt lgkmcnt(0)
	v_mfma_f32_32x32x16_bf16 v[98:113], v[98:101], v[174:177], 0
	v_exp_f32_e32 v198, v82
	v_sub_f32_e32 v82, v88, v231
	v_sub_f32_e32 v83, v83, v231
	v_exp_f32_e32 v200, v82
	v_sub_f32_e32 v82, v89, v231
	v_exp_f32_e32 v199, v83
	v_exp_f32_e32 v234, v82
	ds_read_b128 v[188:191], v233 offset:32
	ds_read_b128 v[114:117], v233 offset:12800
	ds_read_b128 v[192:195], v233 offset:12832
	s_add_i32 s4, s4, 1
	v_pk_add_f32 v[82:83], v[196:197], v[198:199]
	v_pk_add_f32 v[84:85], v[200:201], v[234:235]
	s_waitcnt lgkmcnt(0)
	v_mfma_f32_32x32x16_bf16 v[114:129], v[114:117], v[174:177], 0
	v_add_f32_e64 v236, v82, v84
	v_add_f32_e64 v237, v83, v85
	v_cvt_pk_bf16_f32 v186, v197, v199
	v_cvt_pk_bf16_f32 v187, v201, v235
	v_add_f32_e32 v237, 0, v237
	v_mfma_f32_32x32x16_bf16 v[98:113], v[188:191], v[170:173], v[98:113]
	ds_read_b128 v[82:85], v233 offset:64
	ds_read_b128 v[86:89], v233 offset:12864
	v_add_f32_e32 v197, v236, v237
	v_cvt_pk_bf16_f32 v188, v196, v198
	v_cvt_pk_bf16_f32 v189, v200, v234
	v_mfma_f32_32x32x16_bf16 v[114:129], v[192:195], v[170:173], v[114:129]
	v_sub_f32_e32 v90, v90, v231
	s_waitcnt lgkmcnt(0)
	v_mfma_f32_32x32x16_bf16 v[98:113], v[82:85], v[166:169], v[98:113]
	v_exp_f32_e32 v190, v90
	v_sub_f32_e32 v90, v91, v231
	v_exp_f32_e32 v192, v90
	v_sub_f32_e32 v90, v92, v231
	v_sub_f32_e32 v82, v93, v231
	v_exp_f32_e32 v191, v90
	v_exp_f32_e32 v193, v82
	ds_read_b128 v[82:85], v233 offset:96
	ds_read_b128 v[90:93], v233 offset:12896
	v_mfma_f32_32x32x16_bf16 v[114:129], v[86:89], v[166:169], v[114:129]
	v_add_f32_e64 v194, v190, v192
	v_add_f32_e64 v195, v191, v193
	v_add_f32_e64 v198, v194, v194
	v_add_f32_e64 v199, v194, v195
	v_cvt_pk_bf16_f32 v190, v190, v192
	v_cvt_pk_bf16_f32 v191, v191, v193
	v_sub_f32_e32 v86, v94, v231
	s_waitcnt lgkmcnt(0)
	v_mfma_f32_32x32x16_bf16 v[98:113], v[82:85], v[162:165], v[98:113]
	v_exp_f32_e32 v94, v86
	v_sub_f32_e32 v86, v95, v231
	v_exp_f32_e32 v192, v86
	v_sub_f32_e32 v86, v96, v231
	v_sub_f32_e32 v82, v97, v231
	v_exp_f32_e32 v96, v86
	v_exp_f32_e32 v193, v82
	ds_read_b128 v[82:85], v233 offset:128
	ds_read_b128 v[86:89], v233 offset:12928
	v_add_f32_e32 v95, v94, v192
	v_cvt_pk_bf16_f32 v192, v94, v192
	v_add_f32_e32 v97, v96, v193
	v_mfma_f32_32x32x16_bf16 v[114:129], v[90:93], v[162:165], v[114:129]
	v_cvt_pk_bf16_f32 v193, v96, v193
	v_sub_f32_e32 v66, v66, v231
	v_exp_f32_e32 v94, v66
	v_sub_f32_e32 v66, v67, v231
	v_exp_f32_e32 v96, v66
	v_sub_f32_e32 v66, v68, v231
	v_exp_f32_e32 v198, v66
	s_waitcnt lgkmcnt(0)
	v_mfma_f32_32x32x16_bf16 v[98:113], v[82:85], v[158:161], v[98:113]
	v_sub_f32_e32 v66, v69, v231
	v_exp_f32_e32 v196, v66
	ds_read_b128 v[66:69], v233 offset:160
	ds_read_b128 v[82:85], v233 offset:12960
	v_pk_add_f32 v[90:91], v[94:95], v[96:97]
	v_cvt_pk_bf16_f32 v194, v94, v96
	v_pk_add_f32 v[92:93], v[198:199], v[196:197]
	v_cvt_pk_bf16_f32 v195, v198, v196
	v_mfma_f32_32x32x16_bf16 v[114:129], v[86:89], v[158:161], v[114:129]
	v_add_f32_e64 v90, v90, v92
	v_add_f32_e64 v91, v91, v93
	v_add_f32_e64 v86, v90, v90
	v_add_f32_e64 v87, v90, v91
	v_sub_f32_e32 v70, v70, v231
	v_exp_f32_e32 v88, v70
	v_sub_f32_e32 v70, v71, v231
	s_waitcnt lgkmcnt(0)
	v_mfma_f32_32x32x16_bf16 v[98:113], v[66:69], v[154:157], v[98:113]
	v_exp_f32_e32 v90, v70
	v_sub_f32_e32 v70, v72, v231
	v_sub_f32_e32 v66, v73, v231
	v_exp_f32_e32 v89, v70
	v_exp_f32_e32 v91, v66
	ds_read_b128 v[66:69], v233 offset:192
	ds_read_b128 v[70:73], v233 offset:12992
	v_cvt_pk_bf16_f32 v196, v88, v90
	v_mfma_f32_32x32x16_bf16 v[114:129], v[82:85], v[154:157], v[114:129]
	v_add_f32_e64 v92, v88, v90
	v_add_f32_e64 v93, v89, v91
	v_cvt_pk_bf16_f32 v197, v89, v91
	v_pk_add_f32 v[92:93], v[92:93], v[92:93] op_sel_hi:[0,1]
	v_sub_f32_e32 v74, v74, v231
	s_waitcnt lgkmcnt(0)
	v_mfma_f32_32x32x16_bf16 v[98:113], v[66:69], v[150:153], v[98:113]
	v_exp_f32_e32 v82, v74
	v_sub_f32_e32 v74, v75, v231
	v_exp_f32_e32 v84, v74
	v_sub_f32_e32 v74, v76, v231
	v_sub_f32_e32 v66, v77, v231
	v_exp_f32_e32 v86, v74
	v_exp_f32_e32 v88, v66
	ds_read_b128 v[66:69], v233 offset:224
	ds_read_b128 v[74:77], v233 offset:13024
	v_add_f32_e32 v83, v82, v84
	v_cvt_pk_bf16_f32 v198, v82, v84
	v_add_f32_e32 v85, v86, v88
	v_mfma_f32_32x32x16_bf16 v[114:129], v[70:73], v[150:153], v[114:129]
	v_cvt_pk_bf16_f32 v199, v86, v88
	v_sub_f32_e32 v70, v78, v231
	v_exp_f32_e32 v82, v70
	v_sub_f32_e32 v70, v79, v231
	s_waitcnt lgkmcnt(0)
	v_mfma_f32_32x32x16_bf16 v[98:113], v[66:69], v[146:149], v[98:113]
	v_exp_f32_e32 v84, v70
	v_sub_f32_e32 v70, v80, v231
	v_sub_f32_e32 v66, v81, v231
	v_exp_f32_e32 v92, v70
	v_exp_f32_e32 v86, v66
	ds_read_b128 v[66:69], v233 offset:256
	ds_read_b128 v[70:73], v233 offset:13056
	v_pk_add_f32 v[78:79], v[82:83], v[84:85]
	v_mfma_f32_32x32x16_bf16 v[114:129], v[74:77], v[146:149], v[114:129]
	v_add_f32_e64 v80, v92, v86
	v_add_f32_e64 v81, v93, v87
	v_cvt_pk_bf16_f32 v200, v82, v84
	v_cvt_pk_bf16_f32 v201, v92, v86
	v_add_f32_e64 v78, v78, v80
	v_add_f32_e64 v79, v79, v81
	v_add_f32_e32 v238, v78, v79
	s_waitcnt lgkmcnt(0)
; #define LAS __attribute__((address_space(3)))
; __device__ __forceinline__ unsigned cvt_pk(float lo, float hi) { unsigned r; asm volatile("v_cvt_pk_bf16_f32 %0, %1, %2" : "=v"(r) : "v"(lo), "v"(hi)); return r; }
; __device__ __forceinline__ void attn_unit(LAS unsigned char* lds, int b, int h, int q0, int kbeg, int ntiles, const bf16_t* Q, const bf16_t* K, const bf16_t* Vt, bf16_t* cat) {
;     ...
;         for (int ds = 0; ds < 12; ++ds) {
;             bf16x8 na = ka, nb = kbb;
;             if (ds < 11) { na = *(const LAS bf16x8*)(kb + (ds + 1) * 32); nb = *(const LAS bf16x8*)(kb + 32 * (KP * 2) + (ds + 1) * 32); }
;             pn0 = __builtin_amdgcn_mfma_f32_32x32x16_bf16(ka, qf[ds], pn0, 0, 0, 0);
;             pn1 = __builtin_amdgcn_mfma_f32_32x32x16_bf16(kbb, qf[ds], pn1, 0, 0, 0);
;             if (ds < 8) {
;                 float e[4];
; #pragma unroll
;                 for (int j = 0; j < 4; ++j) { const float v = ds < 4 ? pc0[4 * ds + j] : pc1[4 * (ds - 4) + j]; e[j] = __builtin_amdgcn_exp2f(v - mrun); }
;                 ps += (e[0] + e[1]) + (e[2] + e[3]);
;                 const unsigned w0 = cvt_pk(e[0], e[1]), w1 = cvt_pk(e[2], e[3]);
;                 if ((ds & 1) == 0) { pw[ds >> 1].x = w0; pw[ds >> 1].y = w1; } else { pw[ds >> 1].z = w0; pw[ds >> 1].w = w1; }
;             }
;             ka = na; kbb = nb;
;             __builtin_amdgcn_sched_barrier(0);
;         }
;         lrun += ps;
;         const LAS unsigned char* vb = lds + 2 * AK_BYTES + buf * AV_BYTES + r32 * AV_PITCH + hi * 8;
; #pragma unroll
;         for (int d = 0; d < 4; ++d)
; #pragma unroll
;             for (int ks = 0; ks < 4; ++ks) {
;                 const s16x4 lo = *(const LAS s16x4*)(vb + d * 32 * AV_PITCH + ks * 32), hh = *(const LAS s16x4*)(vb + d * 32 * AV_PITCH + ks * 32 + 16);
;                 const bf16x8 vf = (bf16x8){lo[0], lo[1], lo[2], lo[3], hh[0], hh[1], hh[2], hh[3]};
;                 o[d] = __builtin_amdgcn_mfma_f32_32x32x16_bf16(vf, __builtin_bit_cast(bf16x8, pw[ks]), o[d], 0, 0, 0);
;             }
;         { float mx = fmaxf(pn0[0], pn1[0]);
; #pragma unroll
;           for (int r = 1; r < 16; ++r) mx = fmaxf(mx, fmaxf(pn0[r], pn1[r]));
;           mxc = fmaxf(mx, __shfl_xor(mx, 32)); }
;         if (kt + 1 < ntiles) ASTOREV(buf ^ 1);
;         asm volatile("s_waitcnt vmcnt(0)" ::: "memory");
;         __syncthreads();
	v_mfma_f32_32x32x16_bf16 v[98:113], v[66:69], v[142:145], v[98:113]
	ds_read_b128 v[66:69], v233 offset:288
	ds_read_b128 v[74:77], v233 offset:13088
	v_mfma_f32_32x32x16_bf16 v[114:129], v[70:73], v[142:145], v[114:129]
	s_waitcnt lgkmcnt(0)
	v_mfma_f32_32x32x16_bf16 v[98:113], v[66:69], v[138:141], v[98:113]
	ds_read_b128 v[66:69], v233 offset:320
	ds_read_b128 v[70:73], v233 offset:13120
	v_mfma_f32_32x32x16_bf16 v[114:129], v[74:77], v[138:141], v[114:129]
	s_waitcnt lgkmcnt(0)
	v_mfma_f32_32x32x16_bf16 v[98:113], v[66:69], v[134:137], v[98:113]
	ds_read_b128 v[66:69], v233 offset:352
	ds_read_b128 v[234:237], v233 offset:13152
	v_mfma_f32_32x32x16_bf16 v[114:129], v[70:73], v[134:137], v[114:129]
	s_waitcnt lgkmcnt(0)
	v_mfma_f32_32x32x16_bf16 v[82:97], v[66:69], v[130:133], v[98:113]
	v_mfma_f32_32x32x16_bf16 v[66:81], v[234:237], v[130:133], v[114:129]
	s_mulk_i32 s5, 0x4400
	v_add_u32_e32 v233, s5, v230
	v_add_u32_e32 v102, 0xc800, v233
	ds_read2_b64 v[98:101], v102 offset1:2
	v_add_u32_e32 v110, 0xd800, v233
	v_add_u32_e32 v126, 0xe800, v233
	s_nop 5
	v_max_f32_e32 v239, v67, v67
	v_max_f32_e32 v240, v83, v83
	v_max_f32_e32 v239, v240, v239
	v_max3_f32 v239, v82, v66, v239
	v_add_u32_e32 v233, 0xf800, v233
	s_mulk_i32 s6, 0x4400
	s_waitcnt lgkmcnt(0)
	v_mfma_f32_32x32x16_bf16 v[50:65], v[98:101], v[186:189], v[50:65]
	ds_read2_b64 v[98:101], v102 offset0:4 offset1:6
	v_add_f32_e32 v202, v202, v238
	v_lshl_add_u64 v[214:215], v[214:215], 0, s[38:39]
	v_lshl_add_u64 v[216:217], v[216:217], 0, s[38:39]
	v_lshl_add_u64 v[218:219], v[218:219], 0, s[38:39]
	v_lshl_add_u64 v[220:221], v[220:221], 0, s[38:39]
	v_lshl_add_u64 v[222:223], v[222:223], 0, s[40:41]
	s_cmp_lg_u32 s4, 34
	s_waitcnt lgkmcnt(0)
	v_mfma_f32_32x32x16_bf16 v[50:65], v[98:101], v[190:193], v[50:65]
	ds_read2_b64 v[98:101], v102 offset0:8 offset1:10
	s_waitcnt lgkmcnt(0)
	v_mfma_f32_32x32x16_bf16 v[50:65], v[98:101], v[194:197], v[50:65]
	ds_read2_b64 v[98:101], v102 offset0:12 offset1:14
	ds_read2_b64 v[102:105], v110 offset0:32 offset1:34
	s_waitcnt lgkmcnt(0)
	v_mfma_f32_32x32x16_bf16 v[34:49], v[102:105], v[186:189], v[34:49]
	v_mfma_f32_32x32x16_bf16 v[50:65], v[98:101], v[198:201], v[50:65]
	ds_read2_b64 v[98:101], v110 offset0:36 offset1:38
	ds_read2_b64 v[106:109], v110 offset0:40 offset1:42
	ds_read2_b64 v[110:113], v110 offset0:44 offset1:46
	ds_read2_b64 v[114:117], v126 offset0:64 offset1:66
	ds_read2_b64 v[118:121], v126 offset0:68 offset1:70
	ds_read2_b64 v[122:125], v126 offset0:72 offset1:74
	ds_read2_b64 v[126:129], v126 offset0:76 offset1:78
	ds_read2_b64 v[102:105], v233 offset0:96 offset1:98
	ds_read2_b64 v[234:237], v233 offset0:100 offset1:102
	s_waitcnt lgkmcnt(0)
	v_mfma_f32_32x32x16_bf16 v[34:49], v[98:101], v[190:193], v[34:49]
	v_max_f32_e32 v98, v68, v68
	v_max_f32_e32 v99, v84, v84
	v_max_f32_e32 v98, v99, v98
	v_max_f32_e32 v99, v69, v69
	v_max_f32_e32 v100, v85, v85
	v_max_f32_e32 v99, v100, v99
	v_max3_f32 v98, v239, v98, v99
	v_max_f32_e32 v99, v70, v70
	v_max_f32_e32 v100, v86, v86
	v_max_f32_e32 v99, v100, v99
	v_max_f32_e32 v100, v71, v71
	v_max_f32_e32 v101, v87, v87
	v_max_f32_e32 v100, v101, v100
	v_max3_f32 v98, v98, v99, v100
	v_max_f32_e32 v99, v72, v72
	v_max_f32_e32 v100, v88, v88
	v_max_f32_e32 v99, v100, v99
	v_max_f32_e32 v100, v73, v73
	v_max_f32_e32 v101, v89, v89
	v_max_f32_e32 v100, v101, v100
	v_max3_f32 v98, v98, v99, v100
	v_mfma_f32_32x32x16_bf16 v[18:33], v[114:117], v[186:189], v[18:33]
	v_max_f32_e32 v99, v74, v74
	v_max_f32_e32 v100, v90, v90
	v_max_f32_e32 v99, v100, v99
	v_max_f32_e32 v100, v75, v75
	v_max_f32_e32 v101, v91, v91
	v_max_f32_e32 v100, v101, v100
	v_max3_f32 v98, v98, v99, v100
	v_mfma_f32_32x32x16_bf16 v[2:17], v[102:105], v[186:189], v[2:17]
	v_max_f32_e32 v99, v76, v76
	v_max_f32_e32 v100, v92, v92
	v_max_f32_e32 v99, v100, v99
	v_max_f32_e32 v100, v77, v77
	v_max_f32_e32 v101, v93, v93
	v_max_f32_e32 v100, v101, v100
	v_max3_f32 v98, v98, v99, v100
	v_max_f32_e32 v99, v78, v78
	v_max_f32_e32 v100, v94, v94
	v_max_f32_e32 v99, v100, v99
	v_max_f32_e32 v100, v79, v79
	v_max_f32_e32 v101, v95, v95
	v_mfma_f32_32x32x16_bf16 v[18:33], v[118:121], v[190:193], v[18:33]
	v_max_f32_e32 v100, v101, v100
	v_max3_f32 v98, v98, v99, v100
	v_max_f32_e32 v99, v80, v80
	v_max_f32_e32 v100, v96, v96
	v_max_f32_e32 v99, v100, v99
	v_max_f32_e32 v100, v81, v81
	v_max_f32_e32 v101, v97, v97
	v_mfma_f32_32x32x16_bf16 v[2:17], v[234:237], v[190:193], v[2:17]
	v_max_f32_e32 v100, v101, v100
	v_max3_f32 v98, v98, v99, v100
	ds_bpermute_b32 v99, v209, v98
	s_waitcnt lgkmcnt(0)
	v_max_f32_e32 v99, v99, v99
	v_mfma_f32_32x32x16_bf16 v[34:49], v[106:109], v[194:197], v[34:49]
	ds_read2_b64 v[100:103], v233 offset0:104 offset1:106
	ds_read2_b64 v[104:107], v233 offset0:108 offset1:110
	v_max_f32_e32 v98, v98, v99
	v_add_u32_e32 v99, s6, v232
	v_add_u32_e32 v108, 0xc800, v99
	v_add_u32_e32 v99, 0xea00, v99
	s_waitcnt vmcnt(0)
	ds_write2_b64 v108, v[178:179], v[180:181] offset1:1
	ds_write2_b64 v99, v[182:183], v[184:185] offset1:1
	s_waitcnt vmcnt(0)
	v_mfma_f32_32x32x16_bf16 v[18:33], v[122:125], v[194:197], v[18:33]
	s_waitcnt lgkmcnt(0)
	s_barrier
	v_mfma_f32_32x32x16_bf16 v[2:17], v[100:103], v[194:197], v[2:17]
	v_mfma_f32_32x32x16_bf16 v[34:49], v[110:113], v[198:201], v[34:49]
	v_mfma_f32_32x32x16_bf16 v[18:33], v[126:129], v[198:201], v[18:33]
	v_mfma_f32_32x32x16_bf16 v[2:17], v[104:107], v[198:201], v[2:17]
	s_cbranch_scc0 .LBB0_1845
